# move pooling (P1a) into P2 tail on non-chain WGs
# baseline (speedup 1.0000x reference)
; #define GAS __attribute__((address_space(1)))
; __device__ __forceinline__ unsigned pk2(float lo, float hi) { unsigned r; asm("v_cvt_pk_bf16_f32 %0, %1, %2" : "=v"(r) : "v"(lo), "v"(hi)); return r; }
; __device__ __forceinline__ void prep_phase(Frame& F, CArgs a, int l, unsigned long long& tm_acc) {
;     ...
;     {
;         GAS bf16_t* P = (GAS bf16_t*)(ws + WS_POOL);
;         const int gw = F.blk * 8 + F.wave, NGW = F.G * 8;
;         for (int wi = gw; wi < M; wi += NGW) {
;             const int g = wi & 3, row = (wi >> 2) * 4 + (F.lane >> 4), cg = g * 16 + (F.lane & 15);
;             int t, L; if (row < MC) { t = row & 255; L = CTXL; } else { t = (row - MC) & 2047; L = SEQ; }
;             const GAS bf16_t* zc = Z + (size_t)(row - t) * DIN + cg * 8;
;             float s[8] = {0.f, 0.f, 0.f, 0.f, 0.f, 0.f, 0.f, 0.f}; int cnt = 0;
;             auto body = [&](auto WC) { constexpr int W = decltype(WC)::value;
;                 u32x4 v[W]; float mk[W];
; #pragma unroll
;                 for (int j = 0; j < W; ++j) { const int tt = t - W / 2 + j; const bool ok = tt >= 0 && tt < L; mk[j] = ok ? 1.f : 0.f; cnt += ok ? 1 : 0; v[j] = *(const GAS u32x4*)(zc + (size_t)(ok ? tt : t) * DIN); }
; #pragma unroll
;                 for (int j = 0; j < W; ++j) { s[0] += mk[j] * bflo(v[j].x); s[1] += mk[j] * bfhi(v[j].x); s[2] += mk[j] * bflo(v[j].y); s[3] += mk[j] * bfhi(v[j].y);
;                     s[4] += mk[j] * bflo(v[j].z); s[5] += mk[j] * bfhi(v[j].z); s[6] += mk[j] * bflo(v[j].w); s[7] += mk[j] * bfhi(v[j].w); } };
;             if (g == 0) body(std::integral_constant<int, 2>{}); else if (g == 1) body(std::integral_constant<int, 4>{}); else if (g == 2) body(std::integral_constant<int, 8>{}); else body(std::integral_constant<int, 16>{});
;             const u32x4 sv = *(const GAS u32x4*)(zc + (size_t)t * DIN);
;             const float inv = 1.0f / (float)cnt;
;             u32x4 o; o.x = pk2(s[0] * inv - bflo(sv.x), s[1] * inv - bfhi(sv.x)); o.y = pk2(s[2] * inv - bflo(sv.y), s[3] * inv - bfhi(sv.y));
;             o.z = pk2(s[4] * inv - bflo(sv.z), s[5] * inv - bfhi(sv.z)); o.w = pk2(s[6] * inv - bflo(sv.w), s[7] * inv - bfhi(sv.w));
;             *(GAS u32x4*)(P + (size_t)row * 512 + cg * 8) = o;
;         }
;     }
.LBB0_611:
	s_cmp_le_i32 s96, s4
	s_cselect_b64 s[4:5], -1, 0
	s_and_b64 s[58:59], s[4:5], s[8:9]
	s_andn2_b64 vcc, exec, s[58:59]
	s_cbranch_vccnz .LBB0_677
	s_load_dwordx2 s[6:7], s[0:1], 0x130
	v_readfirstlane_b32 s8, v0
	s_ashr_i32 s4, s8, 6
	s_waitcnt lgkmcnt(0)
	s_add_u32 s22, s6, 0x2a600000
	v_readlane_b32 s5, v254, 54
	s_addc_u32 s23, s7, 0
	s_add_i32 s5, s4, s5
	v_and_b32_e32 v118, 63, v0
	s_branch .LBB0_626

; #define GAS __attribute__((address_space(1)))
; __device__ __forceinline__ unsigned pk2(float lo, float hi) { unsigned r; asm("v_cvt_pk_bf16_f32 %0, %1, %2" : "=v"(r) : "v"(lo), "v"(hi)); return r; }
; __device__ __forceinline__ void prep_phase(Frame& F, CArgs a, int l, unsigned long long& tm_acc) {
;     ...
;         for (int wi = gw; wi < M; wi += NGW) {
;             const int g = wi & 3, row = (wi >> 2) * 4 + (F.lane >> 4), cg = g * 16 + (F.lane & 15);
;             int t, L; if (row < MC) { t = row & 255; L = CTXL; } else { t = (row - MC) & 2047; L = SEQ; }
;             const GAS bf16_t* zc = Z + (size_t)(row - t) * DIN + cg * 8;
;             float s[8] = {0.f, 0.f, 0.f, 0.f, 0.f, 0.f, 0.f, 0.f}; int cnt = 0;
;             auto body = [&](auto WC) { constexpr int W = decltype(WC)::value;
;                 u32x4 v[W]; float mk[W];
; #pragma unroll
;                 for (int j = 0; j < W; ++j) { const int tt = t - W / 2 + j; const bool ok = tt >= 0 && tt < L; mk[j] = ok ? 1.f : 0.f; cnt += ok ? 1 : 0; v[j] = *(const GAS u32x4*)(zc + (size_t)(ok ? tt : t) * DIN); }
; #pragma unroll
;                 for (int j = 0; j < W; ++j) { s[0] += mk[j] * bflo(v[j].x); s[1] += mk[j] * bfhi(v[j].x); s[2] += mk[j] * bflo(v[j].y); s[3] += mk[j] * bfhi(v[j].y);
;                     s[4] += mk[j] * bflo(v[j].z); s[5] += mk[j] * bfhi(v[j].z); s[6] += mk[j] * bflo(v[j].w); s[7] += mk[j] * bfhi(v[j].w); } };
;             if (g == 0) body(std::integral_constant<int, 2>{}); else if (g == 1) body(std::integral_constant<int, 4>{}); else if (g == 2) body(std::integral_constant<int, 8>{}); else body(std::integral_constant<int, 16>{});
;             const u32x4 sv = *(const GAS u32x4*)(zc + (size_t)t * DIN);
;             const float inv = 1.0f / (float)cnt;
;             u32x4 o; o.x = pk2(s[0] * inv - bflo(sv.x), s[1] * inv - bfhi(sv.x)); o.y = pk2(s[2] * inv - bflo(sv.y), s[3] * inv - bfhi(sv.y));
;             o.z = pk2(s[4] * inv - bflo(sv.z), s[5] * inv - bfhi(sv.z)); o.w = pk2(s[6] * inv - bflo(sv.w), s[7] * inv - bfhi(sv.w));
;             *(GAS u32x4*)(P + (size_t)row * 512 + cg * 8) = o;
.LBB0_920:
	s_cmpk_lt_i32 s2, 32
	s_cbranch_scc1 .Lpa_exit
	s_load_dwordx2 s[6:7], s[0:1], 0x130
	v_readfirstlane_b32 s8, v0
	s_ashr_i32 s4, s8, 6
	s_waitcnt lgkmcnt(0)
	s_add_u32 s22, s6, 0x2a600000
	v_readlane_b32 s5, v254, 54
	s_addc_u32 s23, s7, 0
	s_add_i32 s5, s4, s5
	s_addk_i32 s5, 0xff00
	s_cmpk_gt_i32 s5, 0x23ff
	v_and_b32_e32 v118, 63, v0
	s_cbranch_scc1 .Lpa_exit
	s_waitcnt vmcnt(0)
	v_lshlrev_b32_e32 v2, 4, v118
	s_bfe_u32 s10, s8, 0x20006
	v_and_b32_e32 v2, 0xf0, v2
	v_lshl_or_b32 v202, s10, 8, v2
	v_lshl_add_u64 v[2:3], s[6:7], 0, v[202:203]
	s_mov_b64 s[8:9], 0x3c600000
	v_lshrrev_b32_e32 v1, 4, v118
	s_waitcnt vmcnt(16)
	v_lshl_add_u64 v[30:31], s[22:23], 0, v[202:203]
	v_lshl_add_u64 v[32:33], v[2:3], 0, s[8:9]
	s_branch .Lpa_615
.Lpa_614:
	v_lshlrev_b32_e32 v4, 16, v5
	v_fma_f32 v12, v38, v4, v40
	v_and_b32_e32 v4, 0xffff0000, v5
	v_fmac_f32_e32 v41, v38, v4
	v_lshl_add_u64 v[4:5], v[36:37], 0, v[202:203]
	global_load_dwordx4 v[8:11], v[4:5], off
	s_waitcnt vmcnt(14)
	v_cvt_f32_u32_e32 v4, v45
	v_ashrrev_i32_e32 v35, 31, v34
	s_addk_i32 s5, 0x700
	s_cmpk_gt_i32 s5, 0x23ff
	v_div_scale_f32 v5, s[8:9], v4, v4, 1.0
	v_rcp_f32_e32 v13, v5
	s_nop 0
	v_fma_f32 v14, -v5, v13, 1.0
	v_fmac_f32_e32 v13, v14, v13
	v_div_scale_f32 v14, vcc, 1.0, v4, 1.0
	v_mul_f32_e32 v15, v14, v13
	v_fma_f32 v16, -v5, v15, v14
	v_fmac_f32_e32 v15, v16, v13
	v_fma_f32 v5, -v5, v15, v14
	v_div_fmas_f32 v5, v5, v13, v15
	v_div_fixup_f32 v13, v5, v4, 1.0
	s_waitcnt vmcnt(0)
	v_lshlrev_b32_e32 v4, 16, v8
	v_and_b32_e32 v5, 0xffff0000, v8
	v_fma_f32 v4, v42, v13, -v4
	v_fma_f32 v5, v43, v13, -v5
	v_cvt_pk_bf16_f32 v4, v4, v5
	v_lshlrev_b32_e32 v5, 16, v9
	v_fma_f32 v2, v13, v2, -v5
	v_and_b32_e32 v5, 0xffff0000, v9
	v_fma_f32 v3, v13, v3, -v5
	v_cvt_pk_bf16_f32 v5, v2, v3
	v_lshlrev_b32_e32 v2, 16, v10
	v_and_b32_e32 v3, 0xffff0000, v10
	v_fma_f32 v2, v13, v6, -v2
	v_fma_f32 v3, v13, v7, -v3
	v_cvt_pk_bf16_f32 v6, v2, v3
	v_lshlrev_b32_e32 v2, 16, v11
	v_and_b32_e32 v3, 0xffff0000, v11
	v_fma_f32 v2, v12, v13, -v2
	v_fma_f32 v3, v41, v13, -v3
	v_cvt_pk_bf16_f32 v7, v2, v3
	v_lshlrev_b64 v[2:3], 10, v[34:35]
	v_lshl_add_u64 v[2:3], v[32:33], 0, v[2:3]
	global_store_dwordx4 v[2:3], v[4:7], off
	s_cbranch_scc1 .Lpa_exit
.Lpa_615:
	s_and_b32 s8, s5, -4
	s_waitcnt vmcnt(15)
	v_or_b32_e32 v34, s8, v1
	s_movk_i32 s9, 0x400
	v_bitop3_b32 v2, v34, s9, v231 bitop3:0x6c
	v_bitop3_b32 v3, s8, v232, v1 bitop3:0xc8
	v_cmp_gt_i32_e32 vcc, s9, v34
	s_cmp_lt_i32 s10, 2
	s_nop 0
	v_cndmask_b32_e32 v35, v2, v3, vcc
	v_sub_u32_e32 v2, v34, v35
	v_mad_i64_i32 v[36:37], s[8:9], v2, s74, v[30:31]
	s_waitcnt vmcnt(14)
	v_cndmask_b32_e32 v39, v233, v234, vcc
	s_mov_b64 s[8:9], -1
	s_cbranch_scc1 .Lpa_621
	s_cmp_gt_i32 s10, 2
	s_waitcnt vmcnt(13)
	v_add_u32_e32 v53, -4, v35
	v_cmp_lt_u32_e64 s[40:41], 3, v35
	v_add_u32_e32 v51, -3, v35
	v_cmp_lt_u32_e64 s[42:43], 2, v35
	s_waitcnt vmcnt(12)
	v_add_u32_e32 v49, 2, v35
	v_add_u32_e32 v47, 3, v35
	s_cbranch_scc0 .Lpa_618
	v_add_u32_e32 v2, -8, v35
	v_cmp_lt_u32_e32 vcc, 7, v35
	v_cmp_lt_i32_e64 s[38:39], v2, v39
	s_and_b64 vcc, vcc, s[38:39]
	v_add_u32_e32 v4, -7, v35
	v_cndmask_b32_e64 v26, 0, 1, vcc
	v_cndmask_b32_e64 v42, 0, 1.0, vcc
	v_cndmask_b32_e32 v2, v35, v2, vcc
	v_cmp_lt_u32_e32 vcc, 6, v35
	v_cmp_lt_i32_e64 s[38:39], v4, v39
	s_and_b64 vcc, vcc, s[38:39]
	v_mul_i32_i24_e32 v2, 0x6000, v2
	v_cndmask_b32_e32 v4, v35, v4, vcc
	v_ashrrev_i32_e32 v3, 31, v2
	v_mul_i32_i24_e32 v4, 0x6000, v4
	v_lshl_add_u64 v[2:3], v[36:37], 0, v[2:3]
	v_ashrrev_i32_e32 v5, 31, v4
	v_lshl_add_u64 v[4:5], v[36:37], 0, v[4:5]
	global_load_dwordx4 v[66:69], v[2:3], off
	global_load_dwordx4 v[70:73], v[4:5], off
	v_add_u32_e32 v2, -6, v35
	v_cmp_lt_u32_e64 s[38:39], 5, v35
	v_cmp_lt_i32_e64 s[44:45], v2, v39
	v_add_u32_e32 v4, -5, v35
	s_and_b64 s[38:39], s[38:39], s[44:45]
	v_cmp_lt_u32_e64 s[44:45], 4, v35
	v_cmp_lt_i32_e64 s[100:101], v4, v39
	v_cndmask_b32_e64 v2, v35, v2, s[38:39]
	s_and_b64 s[44:45], s[44:45], s[100:101]
	v_mul_i32_i24_e32 v2, 0x6000, v2
	v_cndmask_b32_e64 v4, v35, v4, s[44:45]
	v_ashrrev_i32_e32 v3, 31, v2
	v_cndmask_b32_e64 v27, 0, 1, s[44:45]
	s_waitcnt vmcnt(10)
	v_cndmask_b32_e64 v104, 0, 1.0, s[44:45]
	v_mul_i32_i24_e32 v4, 0x6000, v4
	v_cmp_lt_i32_e64 s[44:45], v53, v39
	v_lshl_add_u64 v[2:3], v[36:37], 0, v[2:3]
	v_ashrrev_i32_e32 v5, 31, v4
	s_and_b64 s[40:41], s[40:41], s[44:45]
	v_cmp_lt_i32_e64 s[44:45], v51, v39
	v_lshl_add_u64 v[4:5], v[36:37], 0, v[4:5]
	global_load_dwordx4 v[74:77], v[2:3], off
	global_load_dwordx4 v[78:81], v[4:5], off
	v_cndmask_b32_e64 v2, v35, v53, s[40:41]
	s_and_b64 s[42:43], s[42:43], s[44:45]
	v_mul_i32_i24_e32 v2, 0x6000, v2
	v_cndmask_b32_e64 v4, v35, v51, s[42:43]
	v_ashrrev_i32_e32 v3, 31, v2
	v_mul_i32_i24_e32 v4, 0x6000, v4
	v_lshl_add_u64 v[2:3], v[36:37], 0, v[2:3]
	v_ashrrev_i32_e32 v5, 31, v4
	v_lshl_add_u64 v[4:5], v[36:37], 0, v[4:5]
	global_load_dwordx4 v[82:85], v[2:3], off
	global_load_dwordx4 v[86:89], v[4:5], off
	v_add_u32_e32 v2, -2, v35
	v_cndmask_b32_e64 v28, 0, 1, s[42:43]
	v_cndmask_b32_e64 v44, 0, 1.0, s[42:43]
	v_cmp_lt_u32_e64 s[42:43], 1, v35
	v_cmp_lt_i32_e64 s[44:45], v2, v39
	s_and_b64 s[42:43], s[42:43], s[44:45]
	v_cmp_le_u32_e64 s[44:45], v35, v39
	v_cndmask_b32_e64 v2, v35, v2, s[42:43]
	v_mul_i32_i24_e32 v2, 0x6000, v2
	v_subbrev_co_u32_e64 v4, s[100:101], 0, v35, s[44:45]
	v_mul_i32_i24_e32 v4, 0x6000, v4
	v_cmp_ne_u32_e64 s[100:101], 0, v35
	v_ashrrev_i32_e32 v3, 31, v2
	v_lshl_add_u64 v[2:3], v[36:37], 0, v[2:3]
	v_cndmask_b32_e64 v4, 0, v4, s[100:101]
	v_ashrrev_i32_e32 v5, 31, v4
	v_lshl_add_u64 v[4:5], v[36:37], 0, v[4:5]
; #define GAS __attribute__((address_space(1)))
; __device__ __forceinline__ void prep_phase(Frame& F, CArgs a, int l, unsigned long long& tm_acc) {
;     ...
;             auto body = [&](auto WC) { constexpr int W = decltype(WC)::value;
;                 u32x4 v[W]; float mk[W];
; #pragma unroll
;                 for (int j = 0; j < W; ++j) { const int tt = t - W / 2 + j; const bool ok = tt >= 0 && tt < L; mk[j] = ok ? 1.f : 0.f; cnt += ok ? 1 : 0; v[j] = *(const GAS u32x4*)(zc + (size_t)(ok ? tt : t) * DIN); }
; #pragma unroll
;                 for (int j = 0; j < W; ++j) { s[0] += mk[j] * bflo(v[j].x); s[1] += mk[j] * bfhi(v[j].x); s[2] += mk[j] * bflo(v[j].y); s[3] += mk[j] * bfhi(v[j].y);
;                     s[4] += mk[j] * bflo(v[j].z); s[5] += mk[j] * bfhi(v[j].z); s[6] += mk[j] * bflo(v[j].w); s[7] += mk[j] * bfhi(v[j].w); } };
;             if (g == 0) body(std::integral_constant<int, 2>{}); else if (g == 1) body(std::integral_constant<int, 4>{}); else if (g == 2) body(std::integral_constant<int, 8>{}); else body(std::integral_constant<int, 16>{});
	s_and_b64 s[44:45], s[100:101], s[44:45]
	global_load_dwordx4 v[90:93], v[2:3], off
	global_load_dwordx4 v[94:97], v[4:5], off
	v_cmp_lt_u32_e64 s[100:101], v35, v39
	v_add_u32_e32 v4, 1, v35
	v_mul_u32_u24_e32 v202, 0x6000, v35
	v_cndmask_b32_e64 v29, 0, 1, s[100:101]
	v_cndmask_b32_e64 v50, 0, 1.0, s[100:101]
	v_cmp_lt_u32_e64 s[100:101], v4, v39
	v_mov_b32_e32 v5, v203
	v_lshl_add_u64 v[2:3], v[36:37], 0, v[202:203]
	v_cndmask_b32_e64 v4, v35, v4, s[100:101]
	v_mul_u32_u24_e32 v4, 0x6000, v4
	v_cndmask_b32_e64 v38, 0, 1, s[100:101]
	v_cndmask_b32_e64 v52, 0, 1.0, s[100:101]
	v_lshl_add_u64 v[4:5], v[36:37], 0, v[4:5]
	v_cmp_lt_u32_e64 s[100:101], v49, v39
	v_cmp_lt_u32_e64 s[50:51], v47, v39
	global_load_dwordx4 v[98:101], v[2:3], off
	global_load_dwordx4 v[6:9], v[4:5], off
	v_cndmask_b32_e64 v2, v35, v49, s[100:101]
	v_cndmask_b32_e64 v4, v35, v47, s[50:51]
	v_mul_u32_u24_e32 v2, 0x6000, v2
	v_mov_b32_e32 v3, v203
	v_mul_u32_u24_e32 v4, 0x6000, v4
	v_mov_b32_e32 v5, v203
	v_lshl_add_u64 v[2:3], v[36:37], 0, v[2:3]
	v_lshl_add_u64 v[4:5], v[36:37], 0, v[4:5]
	global_load_dwordx4 v[14:17], v[2:3], off
	global_load_dwordx4 v[10:13], v[4:5], off
	v_add_u32_e32 v2, 4, v35
	v_add_u32_e32 v4, 5, v35
	v_cndmask_b32_e64 v41, 0, 1, s[50:51]
	v_cndmask_b32_e64 v56, 0, 1.0, s[50:51]
	v_cmp_lt_u32_e64 s[50:51], v2, v39
	v_cmp_lt_u32_e64 s[52:53], v4, v39
	v_mov_b32_e32 v3, v203
	v_cndmask_b32_e64 v2, v35, v2, s[50:51]
	v_cndmask_b32_e64 v4, v35, v4, s[52:53]
	v_mul_u32_u24_e32 v2, 0x6000, v2
	v_mul_u32_u24_e32 v4, 0x6000, v4
	v_mov_b32_e32 v5, v203
	v_cndmask_b32_e64 v48, 0, 1.0, s[44:45]
	v_lshl_add_u64 v[2:3], v[36:37], 0, v[2:3]
	v_lshl_add_u64 v[4:5], v[36:37], 0, v[4:5]
	v_addc_co_u32_e64 v29, s[44:45], 0, v29, s[44:45]
	global_load_dwordx4 v[22:25], v[2:3], off
	global_load_dwordx4 v[18:21], v[4:5], off
	v_add_u32_e32 v2, 6, v35
	v_add_u32_e32 v4, 7, v35
	v_addc_co_u32_e64 v29, s[44:45], v29, v38, s[100:101]
	v_cndmask_b32_e64 v43, 0, 1, s[52:53]
	v_cndmask_b32_e64 v60, 0, 1.0, s[52:53]
	v_cmp_lt_u32_e64 s[52:53], v2, v39
	v_cmp_lt_u32_e64 s[54:55], v4, v39
	v_addc_co_u32_e64 v29, s[44:45], v29, v41, s[50:51]
	s_nop 0
	v_cndmask_b32_e64 v5, 0, 1, s[54:55]
	v_addc_co_u32_e64 v29, s[44:45], v29, v43, s[52:53]
	v_cndmask_b32_e64 v64, 0, 1.0, vcc
	v_addc_co_u32_e32 v5, vcc, v29, v5, vcc
	v_addc_co_u32_e64 v5, vcc, v5, v26, s[38:39]
	v_cndmask_b32_e64 v2, v35, v2, s[52:53]
	v_addc_co_u32_e64 v5, vcc, v5, v27, s[40:41]
	v_cndmask_b32_e64 v4, v35, v4, s[54:55]
	v_mul_u32_u24_e32 v2, 0x6000, v2
	v_mov_b32_e32 v3, v203
	v_addc_co_u32_e64 v45, vcc, v5, v28, s[42:43]
	v_mul_u32_u24_e32 v4, 0x6000, v4
	v_mov_b32_e32 v5, v203
	v_lshl_add_u64 v[2:3], v[36:37], 0, v[2:3]
	v_lshl_add_u64 v[4:5], v[36:37], 0, v[4:5]
	global_load_dwordx4 v[26:29], v[2:3], off
	s_nop 0
	global_load_dwordx4 v[2:5], v[4:5], off
	s_waitcnt vmcnt(15)
	v_lshlrev_b32_e32 v106, 16, v69
	v_and_b32_e32 v107, 0xffff0000, v69
	v_pk_fma_f32 v[106:107], v[42:43], v[106:107], 0 op_sel_hi:[0,1,0]
	s_waitcnt vmcnt(14)
	v_lshlrev_b32_e32 v108, 16, v73
	v_and_b32_e32 v109, 0xffff0000, v73
	v_cndmask_b32_e64 v102, 0, 1.0, s[38:39]
	v_pk_fma_f32 v[106:107], v[64:65], v[108:109], v[106:107] op_sel_hi:[0,1,1]
	s_waitcnt vmcnt(13)
	v_lshlrev_b32_e32 v108, 16, v77
	v_and_b32_e32 v109, 0xffff0000, v77
	v_pk_fma_f32 v[106:107], v[102:103], v[108:109], v[106:107] op_sel_hi:[0,1,1]
	s_waitcnt vmcnt(12)
	v_lshlrev_b32_e32 v108, 16, v81
	v_and_b32_e32 v109, 0xffff0000, v81
	v_pk_fma_f32 v[106:107], v[104:105], v[108:109], v[106:107] op_sel_hi:[0,1,1]
	v_lshlrev_b32_e32 v108, 16, v66
	v_and_b32_e32 v109, 0xffff0000, v66
	v_lshlrev_b32_e32 v66, 16, v67
	v_and_b32_e32 v67, 0xffff0000, v67
	v_lshlrev_b32_e32 v110, 16, v70
	v_and_b32_e32 v111, 0xffff0000, v70
	v_pk_fma_f32 v[66:67], v[42:43], v[66:67], 0 op_sel_hi:[0,1,0]
	v_lshlrev_b32_e32 v70, 16, v71
	v_and_b32_e32 v71, 0xffff0000, v71
	v_pk_fma_f32 v[66:67], v[64:65], v[70:71], v[66:67] op_sel_hi:[0,1,1]
	v_lshlrev_b32_e32 v70, 16, v75
	v_and_b32_e32 v71, 0xffff0000, v75
	v_pk_fma_f32 v[66:67], v[102:103], v[70:71], v[66:67] op_sel_hi:[0,1,1]
	v_lshlrev_b32_e32 v70, 16, v79
	v_and_b32_e32 v71, 0xffff0000, v79
	v_cndmask_b32_e64 v40, 0, 1.0, s[40:41]
	v_pk_fma_f32 v[66:67], v[104:105], v[70:71], v[66:67] op_sel_hi:[0,1,1]
	s_waitcnt vmcnt(11)
	v_lshlrev_b32_e32 v70, 16, v83
	v_and_b32_e32 v71, 0xffff0000, v83
	v_pk_fma_f32 v[66:67], v[40:41], v[70:71], v[66:67] op_sel_hi:[0,1,1]
	v_lshlrev_b32_e32 v70, 16, v68
	v_and_b32_e32 v71, 0xffff0000, v68
	v_pk_fma_f32 v[108:109], v[42:43], v[108:109], 0 op_sel_hi:[0,1,0]
	v_pk_fma_f32 v[42:43], v[42:43], v[70:71], 0 op_sel_hi:[0,1,0]
	v_lshlrev_b32_e32 v68, 16, v72
	v_and_b32_e32 v69, 0xffff0000, v72
	v_pk_fma_f32 v[108:109], v[64:65], v[110:111], v[108:109] op_sel_hi:[0,1,1]
	v_pk_fma_f32 v[42:43], v[64:65], v[68:69], v[42:43] op_sel_hi:[0,1,1]
	v_lshlrev_b32_e32 v64, 16, v76
	v_and_b32_e32 v65, 0xffff0000, v76
	v_lshlrev_b32_e32 v110, 16, v74
	v_and_b32_e32 v111, 0xffff0000, v74
	v_pk_fma_f32 v[42:43], v[102:103], v[64:65], v[42:43] op_sel_hi:[0,1,1]
	v_lshlrev_b32_e32 v64, 16, v80
	v_and_b32_e32 v65, 0xffff0000, v80
	v_pk_fma_f32 v[108:109], v[102:103], v[110:111], v[108:109] op_sel_hi:[0,1,1]
	v_lshlrev_b32_e32 v110, 16, v78
	v_and_b32_e32 v111, 0xffff0000, v78
	v_pk_fma_f32 v[42:43], v[104:105], v[64:65], v[42:43] op_sel_hi:[0,1,1]
	v_lshlrev_b32_e32 v64, 16, v84
	v_and_b32_e32 v65, 0xffff0000, v84
	v_pk_fma_f32 v[108:109], v[104:105], v[110:111], v[108:109] op_sel_hi:[0,1,1]
	v_lshlrev_b32_e32 v110, 16, v82
	v_and_b32_e32 v111, 0xffff0000, v82
	v_pk_fma_f32 v[64:65], v[40:41], v[64:65], v[42:43] op_sel_hi:[0,1,1]
	v_lshlrev_b32_e32 v42, 16, v85
	v_and_b32_e32 v43, 0xffff0000, v85
	v_pk_fma_f32 v[108:109], v[40:41], v[110:111], v[108:109] op_sel_hi:[0,1,1]
	s_waitcnt vmcnt(10)
; #define GAS __attribute__((address_space(1)))
; __device__ __forceinline__ void prep_phase(Frame& F, CArgs a, int l, unsigned long long& tm_acc) {
;     ...
;             auto body = [&](auto WC) { constexpr int W = decltype(WC)::value;
;                 u32x4 v[W]; float mk[W];
; #pragma unroll
;                 for (int j = 0; j < W; ++j) { const int tt = t - W / 2 + j; const bool ok = tt >= 0 && tt < L; mk[j] = ok ? 1.f : 0.f; cnt += ok ? 1 : 0; v[j] = *(const GAS u32x4*)(zc + (size_t)(ok ? tt : t) * DIN); }
; #pragma unroll
;                 for (int j = 0; j < W; ++j) { s[0] += mk[j] * bflo(v[j].x); s[1] += mk[j] * bfhi(v[j].x); s[2] += mk[j] * bflo(v[j].y); s[3] += mk[j] * bfhi(v[j].y);
;                     s[4] += mk[j] * bflo(v[j].z); s[5] += mk[j] * bfhi(v[j].z); s[6] += mk[j] * bflo(v[j].w); s[7] += mk[j] * bfhi(v[j].w); } };
	v_lshlrev_b32_e32 v74, 16, v89
	v_and_b32_e32 v75, 0xffff0000, v89
	v_pk_fma_f32 v[40:41], v[40:41], v[42:43], v[106:107] op_sel_hi:[0,1,1]
	v_cndmask_b32_e64 v46, 0, 1.0, s[42:43]
	s_waitcnt vmcnt(9)
	v_lshlrev_b32_e32 v82, 16, v93
	v_and_b32_e32 v83, 0xffff0000, v93
	v_pk_fma_f32 v[40:41], v[44:45], v[74:75], v[40:41] op_sel_hi:[0,1,1]
	v_lshlrev_b32_e32 v76, 16, v90
	v_and_b32_e32 v77, 0xffff0000, v90
	v_lshlrev_b32_e32 v78, 16, v91
	v_and_b32_e32 v79, 0xffff0000, v91
	s_waitcnt vmcnt(8)
	v_lshlrev_b32_e32 v90, 16, v97
	v_and_b32_e32 v91, 0xffff0000, v97
	v_pk_fma_f32 v[40:41], v[46:47], v[82:83], v[40:41] op_sel_hi:[0,1,1]
	v_pk_fma_f32 v[40:41], v[48:49], v[90:91], v[40:41] op_sel_hi:[0,1,1]
	s_waitcnt vmcnt(7)
	v_lshlrev_b32_e32 v42, 16, v101
	v_and_b32_e32 v43, 0xffff0000, v101
	v_pk_fma_f32 v[40:41], v[50:51], v[42:43], v[40:41] op_sel_hi:[0,1,1]
	s_waitcnt vmcnt(6)
	v_lshlrev_b32_e32 v42, 16, v9
	v_and_b32_e32 v43, 0xffff0000, v9
	v_cndmask_b32_e64 v54, 0, 1.0, s[100:101]
	v_pk_fma_f32 v[40:41], v[52:53], v[42:43], v[40:41] op_sel_hi:[0,1,1]
	s_waitcnt vmcnt(5)
	v_lshlrev_b32_e32 v42, 16, v17
	v_and_b32_e32 v43, 0xffff0000, v17
	v_pk_fma_f32 v[40:41], v[54:55], v[42:43], v[40:41] op_sel_hi:[0,1,1]
	s_waitcnt vmcnt(4)
	v_lshlrev_b32_e32 v42, 16, v13
	v_and_b32_e32 v43, 0xffff0000, v13
	v_cndmask_b32_e64 v58, 0, 1.0, s[50:51]
	v_pk_fma_f32 v[40:41], v[56:57], v[42:43], v[40:41] op_sel_hi:[0,1,1]
	s_waitcnt vmcnt(3)
	v_lshlrev_b32_e32 v42, 16, v25
	v_and_b32_e32 v43, 0xffff0000, v25
	v_pk_fma_f32 v[40:41], v[58:59], v[42:43], v[40:41] op_sel_hi:[0,1,1]
	s_waitcnt vmcnt(2)
	v_lshlrev_b32_e32 v42, 16, v21
	v_and_b32_e32 v43, 0xffff0000, v21
	v_cndmask_b32_e64 v62, 0, 1.0, s[52:53]
	v_lshlrev_b32_e32 v68, 16, v86
	v_and_b32_e32 v69, 0xffff0000, v86
	v_lshlrev_b32_e32 v70, 16, v87
	v_and_b32_e32 v71, 0xffff0000, v87
	v_pk_fma_f32 v[40:41], v[60:61], v[42:43], v[40:41] op_sel_hi:[0,1,1]
	s_waitcnt vmcnt(1)
	v_lshlrev_b32_e32 v42, 16, v29
	v_and_b32_e32 v43, 0xffff0000, v29
	v_pk_fma_f32 v[40:41], v[62:63], v[42:43], v[40:41] op_sel_hi:[0,1,1]
	v_pk_fma_f32 v[42:43], v[44:45], v[68:69], v[108:109] op_sel_hi:[0,1,1]
	v_pk_fma_f32 v[66:67], v[44:45], v[70:71], v[66:67] op_sel_hi:[0,1,1]
	v_lshlrev_b32_e32 v84, 16, v94
	v_and_b32_e32 v85, 0xffff0000, v94
	v_lshlrev_b32_e32 v86, 16, v95
	v_and_b32_e32 v87, 0xffff0000, v95
	v_pk_fma_f32 v[42:43], v[46:47], v[76:77], v[42:43] op_sel_hi:[0,1,1]
	v_pk_fma_f32 v[66:67], v[46:47], v[78:79], v[66:67] op_sel_hi:[0,1,1]
	v_lshlrev_b32_e32 v80, 16, v92
	v_and_b32_e32 v81, 0xffff0000, v92
	v_lshlrev_b32_e32 v92, 16, v98
	v_and_b32_e32 v93, 0xffff0000, v98
	v_lshlrev_b32_e32 v94, 16, v99
	v_and_b32_e32 v95, 0xffff0000, v99
	v_pk_fma_f32 v[42:43], v[48:49], v[84:85], v[42:43] op_sel_hi:[0,1,1]
	v_pk_fma_f32 v[66:67], v[48:49], v[86:87], v[66:67] op_sel_hi:[0,1,1]
	v_pk_fma_f32 v[42:43], v[50:51], v[92:93], v[42:43] op_sel_hi:[0,1,1]
	v_lshlrev_b32_e32 v68, 16, v6
	v_and_b32_e32 v69, 0xffff0000, v6
	v_pk_fma_f32 v[66:67], v[50:51], v[94:95], v[66:67] op_sel_hi:[0,1,1]
	v_lshlrev_b32_e32 v6, 16, v7
	v_and_b32_e32 v7, 0xffff0000, v7
	v_pk_fma_f32 v[42:43], v[52:53], v[68:69], v[42:43] op_sel_hi:[0,1,1]
	v_lshlrev_b32_e32 v68, 16, v14
	v_and_b32_e32 v69, 0xffff0000, v14
	v_pk_fma_f32 v[6:7], v[52:53], v[6:7], v[66:67] op_sel_hi:[0,1,1]
	v_lshlrev_b32_e32 v14, 16, v15
	v_and_b32_e32 v15, 0xffff0000, v15
	v_pk_fma_f32 v[42:43], v[54:55], v[68:69], v[42:43] op_sel_hi:[0,1,1]
	v_lshlrev_b32_e32 v68, 16, v10
	v_and_b32_e32 v69, 0xffff0000, v10
	v_pk_fma_f32 v[6:7], v[54:55], v[14:15], v[6:7] op_sel_hi:[0,1,1]
	v_lshlrev_b32_e32 v10, 16, v11
	v_and_b32_e32 v11, 0xffff0000, v11
	v_pk_fma_f32 v[42:43], v[56:57], v[68:69], v[42:43] op_sel_hi:[0,1,1]
	v_lshlrev_b32_e32 v68, 16, v22
	v_and_b32_e32 v69, 0xffff0000, v22
	v_pk_fma_f32 v[6:7], v[56:57], v[10:11], v[6:7] op_sel_hi:[0,1,1]
	v_lshlrev_b32_e32 v10, 16, v23
	v_and_b32_e32 v11, 0xffff0000, v23
	v_pk_fma_f32 v[42:43], v[58:59], v[68:69], v[42:43] op_sel_hi:[0,1,1]
	v_lshlrev_b32_e32 v68, 16, v18
	v_and_b32_e32 v69, 0xffff0000, v18
	v_pk_fma_f32 v[6:7], v[58:59], v[10:11], v[6:7] op_sel_hi:[0,1,1]
	v_lshlrev_b32_e32 v10, 16, v19
	v_and_b32_e32 v11, 0xffff0000, v19
	v_pk_fma_f32 v[42:43], v[60:61], v[68:69], v[42:43] op_sel_hi:[0,1,1]
	v_lshlrev_b32_e32 v68, 16, v26
	v_and_b32_e32 v69, 0xffff0000, v26
	v_pk_fma_f32 v[6:7], v[60:61], v[10:11], v[6:7] op_sel_hi:[0,1,1]
	v_lshlrev_b32_e32 v10, 16, v27
	v_and_b32_e32 v11, 0xffff0000, v27
	v_cndmask_b32_e64 v38, 0, 1.0, s[54:55]
	v_lshlrev_b32_e32 v72, 16, v88
	v_and_b32_e32 v73, 0xffff0000, v88
	v_pk_fma_f32 v[42:43], v[62:63], v[68:69], v[42:43] op_sel_hi:[0,1,1]
	s_waitcnt vmcnt(0)
	v_lshlrev_b32_e32 v68, 16, v2
	v_and_b32_e32 v69, 0xffff0000, v2
	v_pk_fma_f32 v[6:7], v[62:63], v[10:11], v[6:7] op_sel_hi:[0,1,1]
	v_lshlrev_b32_e32 v2, 16, v3
	v_and_b32_e32 v3, 0xffff0000, v3
	v_pk_fma_f32 v[2:3], v[38:39], v[2:3], v[6:7] op_sel_hi:[0,1,1]
	v_pk_fma_f32 v[6:7], v[44:45], v[72:73], v[64:65] op_sel_hi:[0,1,1]
	v_lshlrev_b32_e32 v88, 16, v96
	v_and_b32_e32 v89, 0xffff0000, v96
	v_pk_fma_f32 v[6:7], v[46:47], v[80:81], v[6:7] op_sel_hi:[0,1,1]
	v_lshlrev_b32_e32 v96, 16, v100
	v_and_b32_e32 v97, 0xffff0000, v100
	v_pk_fma_f32 v[6:7], v[48:49], v[88:89], v[6:7] op_sel_hi:[0,1,1]
	v_pk_fma_f32 v[6:7], v[50:51], v[96:97], v[6:7] op_sel_hi:[0,1,1]
	v_lshlrev_b32_e32 v10, 16, v8
	v_and_b32_e32 v11, 0xffff0000, v8
	v_pk_fma_f32 v[6:7], v[52:53], v[10:11], v[6:7] op_sel_hi:[0,1,1]
	v_lshlrev_b32_e32 v8, 16, v16
	v_and_b32_e32 v9, 0xffff0000, v16
	v_pk_fma_f32 v[6:7], v[54:55], v[8:9], v[6:7] op_sel_hi:[0,1,1]
	v_lshlrev_b32_e32 v8, 16, v12
	v_and_b32_e32 v9, 0xffff0000, v12
	v_pk_fma_f32 v[6:7], v[56:57], v[8:9], v[6:7] op_sel_hi:[0,1,1]
	v_lshlrev_b32_e32 v8, 16, v24
	v_and_b32_e32 v9, 0xffff0000, v24
	v_pk_fma_f32 v[6:7], v[58:59], v[8:9], v[6:7] op_sel_hi:[0,1,1]
	v_lshlrev_b32_e32 v8, 16, v20
	v_and_b32_e32 v9, 0xffff0000, v20
	v_pk_fma_f32 v[6:7], v[60:61], v[8:9], v[6:7] op_sel_hi:[0,1,1]
	v_lshlrev_b32_e32 v8, 16, v28
	v_and_b32_e32 v9, 0xffff0000, v28
	v_pk_fma_f32 v[6:7], v[62:63], v[8:9], v[6:7] op_sel_hi:[0,1,1]
	v_lshlrev_b32_e32 v8, 16, v4
	v_and_b32_e32 v9, 0xffff0000, v4
	v_pk_fma_f32 v[42:43], v[38:39], v[68:69], v[42:43] op_sel_hi:[0,1,1]
	v_pk_fma_f32 v[6:7], v[38:39], v[8:9], v[6:7] op_sel_hi:[0,1,1]
	s_mov_b64 s[8:9], 0

; #define GAS __attribute__((address_space(1)))
; __device__ __forceinline__ unsigned pk2(float lo, float hi) { unsigned r; asm("v_cvt_pk_bf16_f32 %0, %1, %2" : "=v"(r) : "v"(lo), "v"(hi)); return r; }
; __device__ __forceinline__ void xcd_barrier(const XcdBarrier& b) {
;     asm volatile("s_waitcnt vmcnt(0)" ::: "memory");
;     __syncthreads();
;     if (threadIdx.x == 0) {
;         unsigned* bar = b.bar;
;         __builtin_amdgcn_s_waitcnt(0);
;         unsigned nloc = b.st[0], nx = b.st[1];
;         if (nloc == 0u) { xcd_barrier_complete(bar, b.x, nloc, nx); b.st[0] = nloc; b.st[1] = nx; }
; __device__ __forceinline__ void prep_phase(Frame& F, CArgs a, int l, unsigned long long& tm_acc) {
;     ...
;             auto body = [&](auto WC) { constexpr int W = decltype(WC)::value;
;                 u32x4 v[W]; float mk[W];
; #pragma unroll
;                 for (int j = 0; j < W; ++j) { const int tt = t - W / 2 + j; const bool ok = tt >= 0 && tt < L; mk[j] = ok ? 1.f : 0.f; cnt += ok ? 1 : 0; v[j] = *(const GAS u32x4*)(zc + (size_t)(ok ? tt : t) * DIN); }
; #pragma unroll
;                 for (int j = 0; j < W; ++j) { s[0] += mk[j] * bflo(v[j].x); s[1] += mk[j] * bfhi(v[j].x); s[2] += mk[j] * bflo(v[j].y); s[3] += mk[j] * bfhi(v[j].y);
;                     s[4] += mk[j] * bflo(v[j].z); s[5] += mk[j] * bfhi(v[j].z); s[6] += mk[j] * bflo(v[j].w); s[7] += mk[j] * bfhi(v[j].w); } };
;             if (g == 0) body(std::integral_constant<int, 2>{}); else if (g == 1) body(std::integral_constant<int, 4>{}); else if (g == 2) body(std::integral_constant<int, 8>{}); else body(std::integral_constant<int, 16>{});
;             const u32x4 sv = *(const GAS u32x4*)(zc + (size_t)t * DIN);
;             const float inv = 1.0f / (float)cnt;
;             u32x4 o; o.x = pk2(s[0] * inv - bflo(sv.x), s[1] * inv - bfhi(sv.x)); o.y = pk2(s[2] * inv - bflo(sv.y), s[3] * inv - bfhi(sv.y));
;             o.z = pk2(s[4] * inv - bflo(sv.z), s[5] * inv - bfhi(sv.z)); o.w = pk2(s[6] * inv - bflo(sv.w), s[7] * inv - bfhi(sv.w));
;             *(GAS u32x4*)(P + (size_t)row * 512 + cg * 8) = o;
.Lpa_624:
	s_andn2_b64 vcc, exec, s[8:9]
	s_cbranch_vccnz .Lpa_614
	v_add_u32_e32 v2, -2, v35
	v_cmp_lt_u32_e32 vcc, 1, v35
	v_cmp_lt_i32_e64 s[38:39], v2, v39
	s_and_b64 vcc, vcc, s[38:39]
	v_cndmask_b32_e32 v2, v35, v2, vcc
	v_mul_i32_i24_e32 v2, 0x6000, v2
	v_ashrrev_i32_e32 v3, 31, v2
	v_lshl_add_u64 v[2:3], v[36:37], 0, v[2:3]
	v_cmp_le_u32_e64 s[40:41], v35, v39
	global_load_dwordx4 v[6:9], v[2:3], off
	v_cndmask_b32_e64 v20, 0, 1.0, vcc
	v_cndmask_b32_e64 v2, 0, 1, s[40:41]
	v_cmp_eq_u32_e64 s[38:39], 0, v35
	v_addc_co_u32_e32 v2, vcc, 0, v2, vcc
	v_subbrev_co_u32_e64 v4, vcc, 0, v35, s[40:41]
	v_cndmask_b32_e64 v5, v2, 0, s[38:39]
	v_mul_i32_i24_e32 v2, 0x6000, v4
	v_cndmask_b32_e64 v3, 0, 1.0, s[40:41]
	v_cndmask_b32_e64 v2, v2, 0, s[38:39]
	v_cndmask_b32_e64 v22, v3, 0, s[38:39]
	v_ashrrev_i32_e32 v3, 31, v2
	v_lshl_add_u64 v[2:3], v[36:37], 0, v[2:3]
	global_load_dwordx4 v[10:13], v[2:3], off
	v_lshl_add_u64 v[2:3], v[36:37], 0, v[202:203]
	v_cmp_lt_u32_e32 vcc, v35, v39
	global_load_dwordx4 v[14:17], v[2:3], off
	v_add_u32_e32 v2, 1, v35
	v_cndmask_b32_e64 v4, 0, 1, vcc
	v_cndmask_b32_e64 v18, 0, 1.0, vcc
	v_cmp_lt_u32_e32 vcc, v2, v39
	v_mov_b32_e32 v3, v203
	s_waitcnt vmcnt(2)
	v_lshlrev_b32_e32 v24, 16, v9
	v_cndmask_b32_e32 v2, v35, v2, vcc
	v_mul_u32_u24_e32 v2, 0x6000, v2
	v_lshl_add_u64 v[2:3], v[36:37], 0, v[2:3]
	v_addc_co_u32_e64 v45, s[38:39], v5, v4, vcc
	global_load_dwordx4 v[2:5], v[2:3], off
	v_and_b32_e32 v25, 0xffff0000, v9
	v_pk_fma_f32 v[24:25], v[20:21], v[24:25], 0 op_sel_hi:[0,1,0]
	v_cndmask_b32_e64 v38, 0, 1.0, vcc
	s_waitcnt vmcnt(2)
	v_lshlrev_b32_e32 v26, 16, v13
	v_and_b32_e32 v27, 0xffff0000, v13
	v_pk_fma_f32 v[24:25], v[22:23], v[26:27], v[24:25] op_sel_hi:[0,1,1]
	s_waitcnt vmcnt(1)
	v_lshlrev_b32_e32 v26, 16, v17
	v_and_b32_e32 v27, 0xffff0000, v17
	v_pk_fma_f32 v[40:41], v[18:19], v[26:27], v[24:25] op_sel_hi:[0,1,1]
	v_lshlrev_b32_e32 v24, 16, v6
	v_and_b32_e32 v25, 0xffff0000, v6
	v_lshlrev_b32_e32 v6, 16, v7
	v_and_b32_e32 v7, 0xffff0000, v7
	v_pk_fma_f32 v[24:25], v[20:21], v[24:25], 0 op_sel_hi:[0,1,0]
	v_lshlrev_b32_e32 v26, 16, v10
	v_and_b32_e32 v27, 0xffff0000, v10
	v_pk_fma_f32 v[6:7], v[20:21], v[6:7], 0 op_sel_hi:[0,1,0]
	v_lshlrev_b32_e32 v10, 16, v11
	v_and_b32_e32 v11, 0xffff0000, v11
	v_pk_fma_f32 v[24:25], v[22:23], v[26:27], v[24:25] op_sel_hi:[0,1,1]
	v_lshlrev_b32_e32 v26, 16, v14
	v_and_b32_e32 v27, 0xffff0000, v14
	v_pk_fma_f32 v[6:7], v[22:23], v[10:11], v[6:7] op_sel_hi:[0,1,1]
	v_lshlrev_b32_e32 v10, 16, v15
	v_and_b32_e32 v11, 0xffff0000, v15
	v_pk_fma_f32 v[24:25], v[18:19], v[26:27], v[24:25] op_sel_hi:[0,1,1]
	v_pk_fma_f32 v[6:7], v[18:19], v[10:11], v[6:7] op_sel_hi:[0,1,1]
	v_and_b32_e32 v9, 0xffff0000, v12
	s_waitcnt vmcnt(0)
	v_lshlrev_b32_e32 v26, 16, v2
	v_and_b32_e32 v27, 0xffff0000, v2
	v_lshlrev_b32_e32 v2, 16, v3
	v_and_b32_e32 v3, 0xffff0000, v3
	v_pk_fma_f32 v[2:3], v[38:39], v[2:3], v[6:7] op_sel_hi:[0,1,1]
	v_lshlrev_b32_e32 v6, 16, v8
	v_and_b32_e32 v7, 0xffff0000, v8
	v_pk_fma_f32 v[6:7], v[20:21], v[6:7], 0 op_sel_hi:[0,1,0]
	v_lshlrev_b32_e32 v8, 16, v12
	v_pk_fma_f32 v[6:7], v[22:23], v[8:9], v[6:7] op_sel_hi:[0,1,1]
	v_lshlrev_b32_e32 v8, 16, v16
	v_and_b32_e32 v9, 0xffff0000, v16
	v_pk_fma_f32 v[6:7], v[18:19], v[8:9], v[6:7] op_sel_hi:[0,1,1]
	v_lshlrev_b32_e32 v8, 16, v4
	v_and_b32_e32 v9, 0xffff0000, v4
	v_pk_fma_f32 v[42:43], v[38:39], v[26:27], v[24:25] op_sel_hi:[0,1,1]
	v_pk_fma_f32 v[6:7], v[38:39], v[8:9], v[6:7] op_sel_hi:[0,1,1]
	s_branch .Lpa_614
.Lpa_exit:
	v_readlane_b32 s4, v255, 44
	s_add_i32 s4, s4, 6
	s_cmp_lt_i32 s4, s97
	s_cselect_b64 s[6:7], -1, 0
	s_and_b64 s[8:9], s[48:49], s[6:7]
	s_andn2_b64 vcc, exec, s[8:9]
	s_cbranch_vccnz .LBB0_974
	s_waitcnt vmcnt(0)
	s_barrier
	s_and_saveexec_b64 s[8:9], s[88:89]
	s_cbranch_execz .LBB0_973
	v_readlane_b32 s5, v255, 28
	s_waitcnt vmcnt(0) expcnt(0) lgkmcnt(0)
	s_nop 0
	v_mov_b32_e32 v1, s5
	ds_read_b32 v3, v1
	v_readlane_b32 s5, v255, 29
	s_waitcnt lgkmcnt(0)
	v_cmp_ne_u32_e32 vcc, 0, v3
	v_mov_b32_e32 v1, s5
	ds_read_b32 v2, v1
	s_cbranch_vccnz .LBB0_937
	v_readlane_b32 s12, v253, 0
	v_readlane_b32 s13, v253, 1
	s_load_dwordx2 s[10:11], s[12:13], 0x4
	s_mov_b32 s22, 1
	s_waitcnt lgkmcnt(0)
	s_mul_i32 s5, s10, s3
	s_mul_i32 s5, s5, s11
	s_branch .LBB0_925

; #define LAS __attribute__((address_space(3)))
; #define GAS __attribute__((address_space(1)))
; __global__ void __launch_bounds__(512, 2) mk_fwd(Args args_unused) {
;     extern __shared__ __attribute__((aligned(16))) unsigned char lds_raw[];
;     (void)args_unused;
;     CArgs ap = (CArgs)__builtin_amdgcn_kernarg_segment_ptr();
;     Frame F;
;     F.lds = (LAS unsigned char*)lds_raw;
;     F.tid = threadIdx.x; F.lane = F.tid & 63; F.wave = __builtin_amdgcn_readfirstlane(F.tid >> 6);
;     F.blk = blockIdx.x; F.G = gridDim.x; F.ws = (GAS unsigned char*)ap->ws;
;     volatile LAS unsigned* MISC = (volatile LAS unsigned*)(F.lds + MISC_OFF);
;     if (F.tid < 64) MISC[F.tid] = 0u;
;     __syncthreads();
	.amdhsa_kernel _Z6mk_fwd4Args
		.amdhsa_group_segment_fixed_size 0
		.amdhsa_private_segment_fixed_size 0
		.amdhsa_kernarg_size 576
		.amdhsa_user_sgpr_count 2
		.amdhsa_user_sgpr_dispatch_ptr 0
		.amdhsa_user_sgpr_queue_ptr 0
		.amdhsa_user_sgpr_kernarg_segment_ptr 1
		.amdhsa_user_sgpr_dispatch_id 0
		.amdhsa_user_sgpr_kernarg_preload_length 0
		.amdhsa_user_sgpr_kernarg_preload_offset 0
		.amdhsa_user_sgpr_private_segment_size 0
		.amdhsa_uses_dynamic_stack 0
		.amdhsa_enable_private_segment 0
		.amdhsa_system_sgpr_workgroup_id_x 1
		.amdhsa_system_sgpr_workgroup_id_y 0
		.amdhsa_system_sgpr_workgroup_id_z 0
		.amdhsa_system_sgpr_workgroup_info 0
		.amdhsa_system_vgpr_workitem_id 0
		.amdhsa_next_free_vgpr 256
		.amdhsa_next_free_sgpr 102
		.amdhsa_accum_offset 256
		.amdhsa_reserve_vcc 1
		.amdhsa_float_round_mode_32 0
		.amdhsa_float_round_mode_16_64 0
		.amdhsa_float_denorm_mode_32 3
		.amdhsa_float_denorm_mode_16_64 3
		.amdhsa_dx10_clamp 1
		.amdhsa_ieee_mode 1
		.amdhsa_fp16_overflow 0
		.amdhsa_tg_split 0
		.amdhsa_exception_fp_ieee_invalid_op 0
		.amdhsa_exception_fp_denorm_src 0
		.amdhsa_exception_fp_ieee_div_zero 0
		.amdhsa_exception_fp_ieee_overflow 0
		.amdhsa_exception_fp_ieee_underflow 0
		.amdhsa_exception_fp_ieee_inexact 0
		.amdhsa_exception_int_div_zero 0
	.end_amdhsa_kernel

; #define LAS __attribute__((address_space(3)))
; #define GAS __attribute__((address_space(1)))
; __global__ void __launch_bounds__(512, 2) mk_fwd(Args args_unused) {
;     extern __shared__ __attribute__((aligned(16))) unsigned char lds_raw[];
;     (void)args_unused;
;     CArgs ap = (CArgs)__builtin_amdgcn_kernarg_segment_ptr();
;     Frame F;
;     F.lds = (LAS unsigned char*)lds_raw;
;     F.tid = threadIdx.x; F.lane = F.tid & 63; F.wave = __builtin_amdgcn_readfirstlane(F.tid >> 6);
;     F.blk = blockIdx.x; F.G = gridDim.x; F.ws = (GAS unsigned char*)ap->ws;
;     volatile LAS unsigned* MISC = (volatile LAS unsigned*)(F.lds + MISC_OFF);
;     if (F.tid < 64) MISC[F.tid] = 0u;
;     __syncthreads();
amdhsa.kernels:
  - .agpr_count:     0
    .args:
      - .offset:         0
        .size:           320
        .value_kind:     by_value
      - .offset:         320
        .size:           4
        .value_kind:     hidden_block_count_x
      - .offset:         324
        .size:           4
        .value_kind:     hidden_block_count_y
      - .offset:         328
        .size:           4
        .value_kind:     hidden_block_count_z
      - .offset:         332
        .size:           2
        .value_kind:     hidden_group_size_x
      - .offset:         334
        .size:           2
        .value_kind:     hidden_group_size_y
      - .offset:         336
        .size:           2
        .value_kind:     hidden_group_size_z
      - .offset:         338
        .size:           2
        .value_kind:     hidden_remainder_x
      - .offset:         340
        .size:           2
        .value_kind:     hidden_remainder_y
      - .offset:         342
        .size:           2
        .value_kind:     hidden_remainder_z
      - .offset:         360
        .size:           8
        .value_kind:     hidden_global_offset_x
      - .offset:         368
        .size:           8
        .value_kind:     hidden_global_offset_y
      - .offset:         376
        .size:           8
        .value_kind:     hidden_global_offset_z
      - .offset:         384
        .size:           2
        .value_kind:     hidden_grid_dims
      - .offset:         440
        .size:           4
        .value_kind:     hidden_dynamic_lds_size
    .group_segment_fixed_size: 0
    .kernarg_segment_align: 8
    .kernarg_segment_size: 576
    .language:       OpenCL C
    .language_version:
      - 2
      - 0
    .max_flat_workgroup_size: 512
    .name:           _Z6mk_fwd4Args
    .private_segment_fixed_size: 0
    .sgpr_count:     108
    .sgpr_spill_count: 207
    .symbol:         _Z6mk_fwd4Args.kd
    .uniform_work_group_size: 1
    .uses_dynamic_stack: false
    .vgpr_count:     256
    .vgpr_spill_count: 0
    .wavefront_size: 64
